# v23 plus MLA loop: LDS tile writes moved from inside the second P.V MFMA chain to its end
# baseline (speedup 1.0000x reference)
; #define SBAR() __builtin_amdgcn_sched_barrier(0)
; #define SLOAD(i, k0) do { st_[i].vs = *reinterpret_cast<const bf16x8*>(&Vh[(size_t)((k0) + sr) * LDK + sc]); \
;     st_[i].ks = *reinterpret_cast<const bf16x8*>(&Kh[(size_t)((k0) + sr) * LDK + sc]); \
;     if (DQ == 96) st_[i].kr = *reinterpret_cast<const bf16x8*>(&Kr[(size_t)((k0) + sr2) * 32 + sc2]); } while (0)
; #define SWRITE(b, i) do { *(bf16x8*)(V_lds + (b) * SHM_V + vst0) = st_[i].vs; *(bf16x8*)(K_lds + (b) * SHM_K + kst0) = st_[i].ks; \
;     if (DQ == 96) { if (tid < 256) *(bf16x8*)(K_lds + (b) * SHM_K + kst2) = st_[i].kr; } } while (0)
; #define SWAIT() do { if (DQ == 96) asm volatile("s_waitcnt vmcnt(3)" ::: "memory"); else asm volatile("s_waitcnt vmcnt(2)" ::: "memory"); } while (0)
; #define SLOAD(i, k0) do { st_[i].vs = *reinterpret_cast<const bf16x8*>(&Vh[(size_t)((k0) + sr) * LDK + sc]); \
;     st_[i].ks = *reinterpret_cast<const bf16x8*>(&Kh[(size_t)((k0) + sr) * LDK + sc]); \
;     if (DQ == 96) st_[i].kr = *reinterpret_cast<const bf16x8*>(&Kr[(size_t)((k0) + sr2) * 32 + sc2]); } while (0)
; #define SWRITE(b, i) do { *(bf16x8*)(V_lds + (b) * SHM_V + vst0) = st_[i].vs; *(bf16x8*)(K_lds + (b) * SHM_K + kst0) = st_[i].ks; \
;     if (DQ == 96) { if (tid < 256) *(bf16x8*)(K_lds + (b) * SHM_K + kst2) = st_[i].kr; } } while (0)
; #define SWAIT() do { if (DQ == 96) asm volatile("s_waitcnt vmcnt(3)" ::: "memory"); else asm volatile("s_waitcnt vmcnt(2)" ::: "memory"); } while (0)
; template <int DQ, bool WIN, int LDQ, int LDK> ...
;     ...
;         SBAR(); qkt<DQ>(pB0, pB1, K_lds + SHM_K, qr, minit, r32, hi);
;         finish(pA0, pA1); SBAR();
;         SLOAD(SO, KBASE(j + 2)); SBAR();
;         pv(vb0);
;         __syncthreads(); SWAIT(); SWRITE(0, SE);
;         lsum_upd();
.LBB0_1094:
	ds_read_b64_tr_b16 v[40:41], v194 offset:0
	ds_read_b64_tr_b16 v[42:43], v194 offset:0x400
	ds_read_b64_tr_b16 v[44:45], v194 offset:0x800
	ds_read_b64_tr_b16 v[46:47], v194 offset:0xc00
	ds_read_b128 v[198:201], v191 offset:36352
	ds_read_b128 v[80:83], v191 offset:29696
	ds_read_b128 v[202:205], v191 offset:29728
	v_exp_f32_e32 v72, v72
	v_exp_f32_e32 v73, v73
	v_exp_f32_e32 v74, v74
	s_waitcnt lgkmcnt(1)
	v_mfma_f32_32x32x16_bf16 v[96:111], v[80:83], v[134:137], v[48:63]
	v_exp_f32_e32 v75, v75
	v_exp_f32_e32 v197, v64
	v_exp_f32_e32 v206, v77
	v_exp_f32_e32 v207, v78
	v_exp_f32_e32 v208, v79
	v_mfma_f32_32x32x16_bf16 v[80:95], v[198:201], v[134:137], v[48:63]
	ds_read_b128 v[198:201], v191 offset:36384
	s_waitcnt lgkmcnt(1)
	v_mfma_f32_32x32x16_bf16 v[96:111], v[202:205], v[130:133], v[96:111]
	s_waitcnt lgkmcnt(0)
	v_mfma_f32_32x32x16_bf16 v[80:95], v[198:201], v[130:133], v[80:95]
	ds_read_b128 v[198:201], v191 offset:29760
	ds_read_b128 v[202:205], v191 offset:36416
	s_waitcnt lgkmcnt(1)
	v_mfma_f32_32x32x16_bf16 v[96:111], v[198:201], v[126:129], v[96:111]
	s_waitcnt lgkmcnt(0)
	v_mfma_f32_32x32x16_bf16 v[80:95], v[202:205], v[126:129], v[80:95]
	ds_read_b128 v[198:201], v191 offset:29792
	ds_read_b128 v[202:205], v191 offset:36448
	s_waitcnt lgkmcnt(1)
	v_mfma_f32_32x32x16_bf16 v[96:111], v[198:201], v[122:125], v[96:111]
	s_waitcnt lgkmcnt(0)
	v_mfma_f32_32x32x16_bf16 v[80:95], v[202:205], v[122:125], v[80:95]
	ds_read_b128 v[198:201], v191 offset:29824
	ds_read_b128 v[202:205], v191 offset:36480
	s_waitcnt lgkmcnt(1)
	v_mfma_f32_32x32x16_bf16 v[96:111], v[198:201], v[118:121], v[96:111]
	s_waitcnt lgkmcnt(0)
	v_mfma_f32_32x32x16_bf16 v[80:95], v[202:205], v[118:121], v[80:95]
	ds_read_b128 v[198:201], v191 offset:29856
	ds_read_b128 v[202:205], v191 offset:36512
	s_waitcnt lgkmcnt(1)
	v_mfma_f32_32x32x16_bf16 v[96:111], v[198:201], v[114:117], v[96:111]
	v_exp_f32_e32 v198, v65
	v_exp_f32_e32 v199, v66
	v_exp_f32_e32 v200, v67
	v_exp_f32_e32 v201, v68
	v_cvt_pk_bf16_f32 v68, v161, v196
	s_waitcnt lgkmcnt(0)
	v_mfma_f32_32x32x16_bf16 v[80:95], v[202:205], v[114:117], v[80:95]
	v_exp_f32_e32 v202, v69
	v_exp_f32_e32 v203, v70
	v_exp_f32_e32 v204, v71
	v_exp_f32_e32 v205, v76
	v_cvt_pk_bf16_f32 v69, v158, v168
	v_cvt_pk_bf16_f32 v70, v159, v169
	v_cvt_pk_bf16_f32 v71, v160, v195
	v_cvt_pk_bf16_f32 v64, v150, v154
	v_cvt_pk_bf16_f32 v65, v151, v155
	v_cvt_pk_bf16_f32 v66, v152, v156
	v_cvt_pk_bf16_f32 v67, v153, v157
	v_cvt_pk_bf16_f32 v76, v197, v198
	v_cvt_pk_bf16_f32 v77, v199, v200
	v_cvt_pk_bf16_f32 v78, v201, v202
	v_cvt_pk_bf16_f32 v79, v203, v204
	v_cvt_pk_bf16_f32 v72, v72, v73
	v_cvt_pk_bf16_f32 v73, v74, v75
	v_cvt_pk_bf16_f32 v74, v205, v206
	v_cvt_pk_bf16_f32 v75, v207, v208
	global_load_dwordx4 v[154:157], v[164:165], off offset:128
	global_load_dwordx4 v[158:161], v[164:165], off
	global_load_dwordx4 v[150:153], v[166:167], off
	ds_read_b64_tr_b16 v[204:205], v194 offset:0x1000
	ds_read_b64_tr_b16 v[206:207], v194 offset:0x1400
	ds_read_b64_tr_b16 v[208:209], v194 offset:0x1800
	ds_read_b64_tr_b16 v[210:211], v194 offset:0x1c00
	ds_read_b64_tr_b16 v[196:197], v194 offset:0x200
	ds_read_b64_tr_b16 v[198:199], v194 offset:0x600
	ds_read_b64_tr_b16 v[200:201], v194 offset:0xa00
	ds_read_b64_tr_b16 v[202:203], v194 offset:0xe00
	v_mfma_f32_32x32x16_bf16 v[0:15], v[68:71], v[40:43], v[0:15]
	v_mfma_f32_32x32x16_bf16 v[0:15], v[64:67], v[44:47], v[0:15]
	s_waitcnt lgkmcnt(6)
	v_mfma_f32_32x32x16_bf16 v[0:15], v[76:79], v[204:207], v[0:15]
	ds_read_b64_tr_b16 v[204:205], v194 offset:0x1200
	ds_read_b64_tr_b16 v[206:207], v194 offset:0x1600
	s_waitcnt lgkmcnt(6)
	v_mfma_f32_32x32x16_bf16 v[0:15], v[72:75], v[208:211], v[0:15]
	ds_read_b64_tr_b16 v[208:209], v194 offset:0x1a00
	ds_read_b64_tr_b16 v[210:211], v194 offset:0x1e00
	s_waitcnt lgkmcnt(0)
	v_mfma_f32_32x32x16_bf16 v[16:31], v[68:71], v[196:199], v[16:31]
	v_mfma_f32_32x32x16_bf16 v[16:31], v[64:67], v[200:203], v[16:31]
	v_mfma_f32_32x32x16_bf16 v[16:31], v[76:79], v[204:207], v[16:31]
	v_mfma_f32_32x32x16_bf16 v[16:31], v[72:75], v[208:211], v[16:31]
	s_waitcnt vmcnt(3)
	ds_write_b128 v192, v[138:141]
	ds_write_b128 v193, v[142:145] offset:16384
	ds_write_b128 v112, v[146:149] offset:16512

; #define SBAR() __builtin_amdgcn_sched_barrier(0)
; #define SLOAD(i, k0) do { st_[i].vs = *reinterpret_cast<const bf16x8*>(&Vh[(size_t)((k0) + sr) * LDK + sc]); \
;     st_[i].ks = *reinterpret_cast<const bf16x8*>(&Kh[(size_t)((k0) + sr) * LDK + sc]); \
;     if (DQ == 96) st_[i].kr = *reinterpret_cast<const bf16x8*>(&Kr[(size_t)((k0) + sr2) * 32 + sc2]); } while (0)
; #define SWRITE(b, i) do { *(bf16x8*)(V_lds + (b) * SHM_V + vst0) = st_[i].vs; *(bf16x8*)(K_lds + (b) * SHM_K + kst0) = st_[i].ks; \
;     if (DQ == 96) { if (tid < 256) *(bf16x8*)(K_lds + (b) * SHM_K + kst2) = st_[i].kr; } } while (0)
; #define SWAIT() do { if (DQ == 96) asm volatile("s_waitcnt vmcnt(3)" ::: "memory"); else asm volatile("s_waitcnt vmcnt(2)" ::: "memory"); } while (0)
; #define SLOAD(i, k0) do { st_[i].vs = *reinterpret_cast<const bf16x8*>(&Vh[(size_t)((k0) + sr) * LDK + sc]); \
;     st_[i].ks = *reinterpret_cast<const bf16x8*>(&Kh[(size_t)((k0) + sr) * LDK + sc]); \
;     if (DQ == 96) st_[i].kr = *reinterpret_cast<const bf16x8*>(&Kr[(size_t)((k0) + sr2) * 32 + sc2]); } while (0)
; #define SWRITE(b, i) do { *(bf16x8*)(V_lds + (b) * SHM_V + vst0) = st_[i].vs; *(bf16x8*)(K_lds + (b) * SHM_K + kst0) = st_[i].ks; \
;     if (DQ == 96) { if (tid < 256) *(bf16x8*)(K_lds + (b) * SHM_K + kst2) = st_[i].kr; } } while (0)
; #define SWAIT() do { if (DQ == 96) asm volatile("s_waitcnt vmcnt(3)" ::: "memory"); else asm volatile("s_waitcnt vmcnt(2)" ::: "memory"); } while (0)
; template <int DQ, bool WIN, int LDQ, int LDK> ...
;     ...
;         if (j + 3 < NT) SLOAD(SE, KBASE(j + 3)); SBAR();
;         pv(vb0 + SHM_V);
;         __syncthreads(); SWAIT(); SWRITE(1, SO);
;         lsum_upd();
.LBB0_1098:
	ds_read_b64_tr_b16 v[204:205], v190 offset:0x1000
	ds_read_b64_tr_b16 v[206:207], v190 offset:0x1400
	ds_read_b64_tr_b16 v[208:209], v190 offset:0x1800
	ds_read_b64_tr_b16 v[210:211], v190 offset:0x1c00
	ds_read_b64_tr_b16 v[196:197], v190 offset:0x200
	ds_read_b64_tr_b16 v[198:199], v190 offset:0x600
	ds_read_b64_tr_b16 v[200:201], v190 offset:0xa00
	ds_read_b64_tr_b16 v[202:203], v190 offset:0xe00
	v_mfma_f32_32x32x16_bf16 v[0:15], v[80:83], v[40:43], v[0:15]
	v_mfma_f32_32x32x16_bf16 v[0:15], v[84:87], v[44:47], v[0:15]
	s_waitcnt lgkmcnt(6)
	v_mfma_f32_32x32x16_bf16 v[0:15], v[88:91], v[204:207], v[0:15]
	ds_read_b64_tr_b16 v[204:205], v190 offset:0x1200
	ds_read_b64_tr_b16 v[206:207], v190 offset:0x1600
	s_waitcnt lgkmcnt(6)
	v_mfma_f32_32x32x16_bf16 v[0:15], v[92:95], v[208:211], v[0:15]
	ds_read_b64_tr_b16 v[208:209], v190 offset:0x1a00
	ds_read_b64_tr_b16 v[210:211], v190 offset:0x1e00
	s_waitcnt lgkmcnt(0)
	v_mfma_f32_32x32x16_bf16 v[16:31], v[80:83], v[196:199], v[16:31]
	v_mfma_f32_32x32x16_bf16 v[16:31], v[84:87], v[200:203], v[16:31]
	v_mfma_f32_32x32x16_bf16 v[16:31], v[88:91], v[204:207], v[16:31]
	v_mfma_f32_32x32x16_bf16 v[16:31], v[92:95], v[208:211], v[16:31]
	s_waitcnt vmcnt(3)
	ds_write_b128 v192, v[154:157] offset:8192
	ds_write_b128 v193, v[158:161] offset:29696
	ds_write_b128 v112, v[150:153] offset:29824
	s_branch .LBB0_1093
